# v19 + weight-conversion phase: the W_gu and W_in tile loaders issue all 8 row loads and 8 gain loads together and wait once (hipcc had serialized 8-16 HBM round trips per tile); numerics unchanged
# speedup vs baseline: 1.0288x; 1.0018x over previous
; #define LAS __attribute__((address_space(3)))
; __device__ __forceinline__ int otid() { int t = threadIdx.x; asm volatile("" : "+v"(t)); return t; }
; __device__ __forceinline__ unsigned pk2(float lo, float hi) { f32x2 f = {lo, hi}; bf16x2_t v = __builtin_convertvector(f, bf16x2_t); return __builtin_bit_cast(unsigned, v); }
; __device__ __forceinline__ void wtile(LAS float* tile, const float* src, int lds_src, const float* gain, bf16_t* dst, int K, int n0, int k0, int c0, int nvalid) {
;     const int tid = otid();
;     __syncthreads();
; #pragma unroll
;     for (int i = 0; i < 8; ++i) {
;         const int kk = (tid >> 6) + 8 * i, c = tid & 63;
;         float v = 0.f;
;         if (c0 + c < nvalid) { v = src[(size_t)(k0 + kk) * lds_src + c0 + c]; if (gain) v *= gain[k0 + kk]; }
;         tile[kk * 65 + c] = v;
;     }
;     __syncthreads();
;     const int n = tid >> 3, kc = (tid & 7) * 8;
;     float f[8];
; #pragma unroll
;     for (int j = 0; j < 8; ++j) f[j] = tile[(kc + j) * 65 + n];
;     u32x4 w; w.x = pk2(f[0], f[1]); w.y = pk2(f[2], f[3]); w.z = pk2(f[4], f[5]); w.w = pk2(f[6], f[7]);
;     *(u32x4*)(dst + (size_t)(n0 + n) * K + k0 + kc) = w;
; __device__ __forceinline__ void phase_weights(LAS unsigned char* lds, const Params& P) {
;     ...
;         } else if ((r -= T_OUT) < T_GU) { const int nb = r / 16, kb = r % 16;
;             const int j = nb >> 2, qd = nb & 3; const float* src = (qd < 2 ? P.in[26] : P.in[27]) + (size_t)l * DM * DFF;
;             wtile(tile, src, DFF, P.in[25] + l * DM, (bf16_t*)(ws + WS_WGU) + (size_t)l * 2 * DFF * DM, DM, nb * 64, kb * 64, j * 128 + (qd & 1) * 64, DFF);
.LBB0_27:
	s_andn2_b64 vcc, exec, s[0:1]
	s_cbranch_vccnz .LBB0_45
	s_add_i32 s16, s4, 0xfffffb80
	s_bitcmp0_b32 s4, 5
	s_cselect_b32 s1, s84, s86
	s_cselect_b32 s0, s85, s87
	s_add_u32 s27, s1, s24
	s_addc_u32 s30, s0, s5
	s_lshl_b32 s0, s18, 10
	s_ashr_i32 s1, s0, 31
	s_lshl_b64 s[0:1], s[0:1], 2
	s_add_u32 s28, s82, s0
	s_addc_u32 s29, s83, s1
	s_lshl_b32 s0, s4, 6
	s_lshl_b32 s26, s16, 2
	s_and_b32 s25, s0, 0x3c0
	s_lshl_b32 s0, s16, 1
	s_and_b32 s0, s0, 0x7fffff80
	s_and_b32 s1, s26, 64
	s_or_b32 s16, s0, s1
	v_mov_b32_e32 v10, v203
	s_lshl_b64 s[0:1], s[16:17], 2
	s_add_u32 s0, s27, s0
	v_and_b32_e32 v12, 63, v10
	v_ashrrev_i32_e32 v11, 6, v10
	s_addc_u32 s1, s30, s1
	v_lshlrev_b32_e32 v6, 2, v12
	v_lshl_add_u64 v[2:3], s[0:1], 0, v[6:7]
	v_add_u32_e32 v4, s25, v11
	v_mad_i64_i32 v[8:9], s[0:1], v4, s42, v[2:3]
	s_barrier
	global_load_dword v6, v[8:9], off
	v_add_u32_e32 v5, 8, v4
	v_mad_i64_i32 v[14:15], s[0:1], v5, s42, v[2:3]
	global_load_dword v13, v[14:15], off
	v_add_u32_e32 v5, 16, v4
	v_mad_i64_i32 v[24:25], s[0:1], v5, s42, v[2:3]
	global_load_dword v16, v[24:25], off
	v_add_u32_e32 v5, 24, v4
	v_mad_i64_i32 v[14:15], s[0:1], v5, s42, v[2:3]
	global_load_dword v17, v[14:15], off
	v_add_u32_e32 v5, 32, v4
	v_mad_i64_i32 v[24:25], s[0:1], v5, s42, v[2:3]
	global_load_dword v18, v[24:25], off
	v_add_u32_e32 v5, 40, v4
	v_mad_i64_i32 v[14:15], s[0:1], v5, s42, v[2:3]
	global_load_dword v19, v[14:15], off
	v_add_u32_e32 v5, 48, v4
	v_mad_i64_i32 v[24:25], s[0:1], v5, s42, v[2:3]
	global_load_dword v20, v[24:25], off
	v_add_u32_e32 v5, 56, v4
	v_mad_i64_i32 v[14:15], s[0:1], v5, s42, v[2:3]
	global_load_dword v21, v[14:15], off
	v_lshl_add_u32 v5, v12, 2, 0
	v_mul_lo_u32 v11, v11, s40
	v_add_u32_e32 v5, v5, v11
	s_andn2_b64 vcc, exec, s[6:7]
	s_cbranch_vccnz .Lwt1_write
	v_mov_b32_e32 v8, v4
	v_ashrrev_i32_e32 v9, 31, v4
	v_lshl_add_u64 v[8:9], v[8:9], 2, s[28:29]
	global_load_dword v22, v[8:9], off
	global_load_dword v23, v[8:9], off offset:32
	global_load_dword v24, v[8:9], off offset:64
	global_load_dword v25, v[8:9], off offset:96
	global_load_dword v26, v[8:9], off offset:128
	global_load_dword v27, v[8:9], off offset:160
	global_load_dword v28, v[8:9], off offset:192
	global_load_dword v29, v[8:9], off offset:224
	s_waitcnt vmcnt(0)
	v_mul_f32_e32 v6, v6, v22
	v_mul_f32_e32 v13, v13, v23
	v_mul_f32_e32 v16, v16, v24
	v_mul_f32_e32 v17, v17, v25
	v_mul_f32_e32 v18, v18, v26
	v_mul_f32_e32 v19, v19, v27
	v_mul_f32_e32 v20, v20, v28
	v_mul_f32_e32 v21, v21, v29
.Lwt1_write:
	s_waitcnt vmcnt(0)
	ds_write_b32 v5, v6
	ds_write_b32 v5, v13 offset:2080
	ds_write_b32 v5, v16 offset:4160
	ds_write_b32 v5, v17 offset:6240
	ds_write_b32 v5, v18 offset:8320
	ds_write_b32 v5, v19 offset:10400
	ds_write_b32 v5, v20 offset:12480
	ds_write_b32 v5, v21 offset:14560
	v_lshlrev_b32_e32 v2, 3, v10
	v_ashrrev_i32_e32 v12, 3, v10
	v_and_b32_e32 v6, 56, v2
	v_lshlrev_b32_e32 v2, 2, v12
	v_mul_u32_u24_e32 v3, 0x104, v6
	v_add3_u32 v8, 0, v2, v3
	s_waitcnt lgkmcnt(0)
	s_barrier
	ds_read2_b32 v[2:3], v8 offset1:65
	ds_read2_b32 v[4:5], v8 offset0:130 offset1:195
	v_add_u32_e32 v10, 0x400, v8
	ds_read2_b32 v[8:9], v10 offset0:4 offset1:69
	ds_read2_b32 v[10:11], v10 offset0:134 offset1:199
	s_add_u32 s0, s34, s24
	s_addc_u32 s1, s35, s5
	s_and_b32 s5, s26, 0x7fffffc0
	s_waitcnt lgkmcnt(3)
	v_cvt_pk_bf16_f32 v2, v2, v3
	s_waitcnt lgkmcnt(2)
	v_cvt_pk_bf16_f32 v3, v4, v5
	s_waitcnt lgkmcnt(1)
	v_cvt_pk_bf16_f32 v4, v8, v9
	v_add_u32_e32 v8, s5, v12
	v_ashrrev_i32_e32 v9, 31, v8
	v_lshlrev_b64 v[8:9], 11, v[8:9]
	v_lshl_add_u64 v[8:9], s[0:1], 0, v[8:9]
	s_lshl_b32 s16, s25, 1
	s_waitcnt lgkmcnt(0)
	v_cvt_pk_bf16_f32 v5, v10, v11
	v_lshl_add_u64 v[8:9], v[8:9], 0, s[16:17]

; __device__ __forceinline__ void wtile(LAS float* tile, const float* src, int lds_src, const float* gain, bf16_t* dst, int K, int n0, int k0, int c0, int nvalid) {
;     ...
;     for (int i = 0; i < 8; ++i) {
;         const int kk = (tid >> 6) + 8 * i, c = tid & 63;
;         float v = 0.f;
;         if (c0 + c < nvalid) { v = src[(size_t)(k0 + kk) * lds_src + c0 + c]; if (gain) v *= gain[k0 + kk]; }
;         tile[kk * 65 + c] = v;
;     }
; __device__ __forceinline__ void phase_weights(LAS unsigned char* lds, const Params& P) {
;     ...
;         if (r < T_IN) { const int nb = r / 16, kb = r % 16;
;             wtile(tile, P.in[3] + (size_t)l * DM * DIN, DIN, P.in[2] + l * DM, (bf16_t*)(ws + WS_WIN) + (size_t)l * DINP * DM, DM, nb * 64, kb * 64, nb * 64, DIN);
.LBB0_49:
	s_andn2_b64 vcc, exec, s[0:1]
	s_cbranch_vccnz .LBB0_22
	s_bfe_u32 s0, s4, 0x4001b
	s_add_i32 s0, s4, s0
	s_sext_i32_i16 s5, s0
	s_and_b32 s0, s0, 0xfff0
	s_sub_i32 s0, s4, s0
	s_mul_i32 s1, s18, 0xdb0000
	s_sext_i32_i16 s4, s0
	s_mul_hi_i32 s0, s18, 0xdb0000
	s_add_u32 s16, s54, s1
	s_addc_u32 s19, s55, s0
	s_lshl_b32 s0, s18, 10
	s_ashr_i32 s1, s0, 31
	s_lshl_b64 s[0:1], s[0:1], 2
	s_add_u32 s28, s52, s0
	s_addc_u32 s29, s53, s1
	s_lshl_b32 s0, s5, 2
	s_and_b32 s26, s0, 0xffffffc0
	s_ashr_i32 s27, s26, 31
	s_lshl_b32 s24, s4, 6
	v_mov_b32_e32 v10, v203
	s_lshl_b64 s[4:5], s[26:27], 2
	s_add_u32 s4, s16, s4
	v_and_b32_e32 v3, 63, v10
	v_bfi_b32 v4, 63, v10, s0
	s_addc_u32 s5, s19, s5
	v_lshlrev_b32_e32 v6, 2, v3
	v_cmp_gt_i32_e64 s[0:1], s43, v4
	v_lshl_add_u64 v[4:5], s[4:5], 0, v[6:7]
	v_cndmask_b32_e64 v6, 0, 1, s[12:13]
	v_ashrrev_i32_e32 v2, 6, v10
	v_mov_b32_e32 v11, 0
	v_cmp_ne_u32_e64 s[4:5], 1, v6
	v_mov_b32_e32 v12, 0
	s_barrier
	v_mov_b32_e32 v16, 0
	v_mov_b32_e32 v17, 0
	v_mov_b32_e32 v18, 0
	v_mov_b32_e32 v19, 0
	v_mov_b32_e32 v20, 0
	v_mov_b32_e32 v21, 0
	v_lshl_add_u32 v3, v3, 2, 0
	v_mul_lo_u32 v6, v2, s40
	v_add_u32_e32 v6, v3, v6
	v_add_u32_e32 v8, s24, v2
	s_and_saveexec_b64 s[30:31], s[0:1]
	s_cbranch_execz .Lwt2_write
	v_mad_i64_i32 v[14:15], s[46:47], v8, s44, v[4:5]
	global_load_dword v12, v[14:15], off
	v_add_u32_e32 v3, 8, v8
	v_mad_i64_i32 v[24:25], s[46:47], v3, s44, v[4:5]
	global_load_dword v11, v[24:25], off
	v_add_u32_e32 v3, 16, v8
	v_mad_i64_i32 v[14:15], s[46:47], v3, s44, v[4:5]
	global_load_dword v16, v[14:15], off
	v_add_u32_e32 v3, 24, v8
	v_mad_i64_i32 v[24:25], s[46:47], v3, s44, v[4:5]
	global_load_dword v17, v[24:25], off
	v_add_u32_e32 v3, 32, v8
	v_mad_i64_i32 v[14:15], s[46:47], v3, s44, v[4:5]
	global_load_dword v18, v[14:15], off
	v_add_u32_e32 v3, 40, v8
	v_mad_i64_i32 v[24:25], s[46:47], v3, s44, v[4:5]
	global_load_dword v19, v[24:25], off
	v_add_u32_e32 v3, 48, v8
	v_mad_i64_i32 v[14:15], s[46:47], v3, s44, v[4:5]
	global_load_dword v20, v[14:15], off
	v_add_u32_e32 v3, 56, v8
	v_mad_i64_i32 v[24:25], s[46:47], v3, s44, v[4:5]
	global_load_dword v21, v[24:25], off
	s_and_b64 vcc, exec, s[4:5]
	s_cbranch_vccnz .Lwt2_write
	v_ashrrev_i32_e32 v9, 31, v8
	v_lshl_add_u64 v[8:9], v[8:9], 2, s[28:29]
	global_load_dword v22, v[8:9], off
	global_load_dword v23, v[8:9], off offset:32
	global_load_dword v24, v[8:9], off offset:64
	global_load_dword v25, v[8:9], off offset:96
	global_load_dword v26, v[8:9], off offset:128
	global_load_dword v27, v[8:9], off offset:160
	global_load_dword v28, v[8:9], off offset:192
	global_load_dword v29, v[8:9], off offset:224
	s_waitcnt vmcnt(0)
	v_mul_f32_e32 v12, v12, v22
	v_mul_f32_e32 v11, v11, v23
	v_mul_f32_e32 v16, v16, v24
	v_mul_f32_e32 v17, v17, v25
	v_mul_f32_e32 v18, v18, v26
	v_mul_f32_e32 v19, v19, v27
	v_mul_f32_e32 v20, v20, v28
	v_mul_f32_e32 v21, v21, v29
.Lwt2_write:
	s_or_b64 exec, exec, s[30:31]
	s_waitcnt vmcnt(0)
	ds_write_b32 v6, v12
	ds_write_b32 v6, v11 offset:2080
	ds_write_b32 v6, v16 offset:4160
	ds_write_b32 v6, v17 offset:6240
	ds_write_b32 v6, v18 offset:8320
	ds_write_b32 v6, v19 offset:10400
	ds_write_b32 v6, v20 offset:12480
	v_mov_b32_e32 v8, v21
	s_branch .LBB0_21
